# attention: waves 0-3 defer 4 and waves 4-7 defer 8 PV MFMAs across the step barrier, first fragments fetched under them
# baseline (speedup 1.0000x reference)
.Lnd_107:
	s_and_b32 s33, s42, 1
	s_mul_i32 s6, s33, 0x9000
	v_add_u32_e32 v199, s6, v187
	v_add_u32_e32 v198, s6, v188
	s_mov_b64 s[54:55], exec
	v_readfirstlane_b32 s4, v186
	s_bitcmp1_b32 s4, 8
	s_cbranch_scc1 .Lab_B
	ds_read_b128 v[252:255], v199
	ds_read_b128 v[208:211], v193
	ds_read_b128 v[212:215], v199 offset:32
	s_cmp_eq_u32 s42, 0
	s_cbranch_scc1 .Lab_A0
	v_mfma_f32_32x32x16_bf16 v[128:143], v[220:223], v[204:207], v[128:143]
	v_mfma_f32_32x32x16_bf16 v[96:111], v[228:231], v[204:207], v[96:111]
	v_mfma_f32_32x32x16_bf16 v[64:79], v[236:239], v[204:207], v[64:79]
	v_mfma_f32_32x32x16_bf16 v[32:47], v[248:251], v[204:207], v[32:47]

.Lqt_pf_1:
	s_add_i32 s10, s42, 2
	s_mov_b32 s11, 0
	s_lshl_b64 s[4:5], s[10:11], 13
	s_add_u32 s4, s50, s4
	s_addc_u32 s5, s51, s5
	s_lshl_b64 s[8:9], s[10:11], 14
	s_add_u32 s8, s52, s8
	v_lshl_add_u64 v[252:253], s[4:5], 0, v[176:177]
	s_addc_u32 s9, s53, s9
	global_load_dwordx4 v[160:163], v[252:253], off
	v_add_co_u32_e32 v252, vcc, 0x100000, v252
	v_lshl_add_u64 v[254:255], s[8:9], 0, v[176:177]
	s_nop 0
	v_addc_co_u32_e32 v253, vcc, 0, v253, vcc
	global_load_dwordx4 v[168:171], v[252:253], off
	v_add_co_u32_e32 v252, vcc, 0x2000, v254
	global_load_dwordx4 v[164:167], v[254:255], off
	s_nop 0
	v_addc_co_u32_e32 v253, vcc, 0, v255, vcc
	global_load_dwordx4 v[172:175], v[252:253], off
	v_mfma_f32_32x32x16_bf16 v[128:143], v[216:219], v[200:203], v[128:143]
	v_mfma_f32_32x32x16_bf16 v[96:111], v[224:227], v[200:203], v[96:111]
	v_mfma_f32_32x32x16_bf16 v[64:79], v[232:235], v[200:203], v[64:79]
	v_mfma_f32_32x32x16_bf16 v[32:47], v[244:247], v[200:203], v[32:47]
	s_add_i32 s4, s42, 1
	s_cmp_lt_u32 s4, s98
	s_cbranch_scc1 .LBB0_116
	s_nop 1
	v_mfma_f32_32x32x16_bf16 v[128:143], v[220:223], v[204:207], v[128:143]
	v_mfma_f32_32x32x16_bf16 v[96:111], v[228:231], v[204:207], v[96:111]
	v_mfma_f32_32x32x16_bf16 v[64:79], v[236:239], v[204:207], v[64:79]
	v_mfma_f32_32x32x16_bf16 v[32:47], v[248:251], v[204:207], v[32:47]
	s_branch .LBB0_116
